# merge GEMM K-seam hook: the 32 gate loads issued together with counted vmcnt instead of 16 load-wait round trips
# speedup vs baseline: 1.0114x; 1.0114x over previous
;     static __device__ __forceinline__ float gv(unsigned long long gw, int i) { return __uint_as_float((unsigned)((gw >> (16 * i)) & 0xffffull) << 16); }
;     __device__ __forceinline__ void khook(f32x4 (&acc)[2][2][4][2], const Unit& u, int t, int wr, int wc, int fr, int fq) const {
;         const int col0 = u.pn * BM + wc * 32 + 4 * fq; const int br = (t == 8) ? 0 : 1;
; #pragma unroll
;         for (int ai = 0; ai < 1; ++ai)
; #pragma unroll
;             for (int m = 0; m < 4; ++m) { const size_t row = (size_t)(u.pm * HALF + wr * 64 + m * 16 + fr);
; #pragma unroll
;                 for (int bj = 0; bj < 2; ++bj)
; #pragma unroll
;                     for (int n = 0; n < 2; ++n) { const int c = col0 + bj * HALF + n * 16; const bf16_t* gp = G + row * ldg + c + br * 1024;
;                         const unsigned long long ga = *(const unsigned long long*)gp, gb = *(const unsigned long long*)(gp + 1024);
; #pragma unroll
;                         for (int i = 0; i < 4; ++i) acc[ai][bj][m][n][i] *= gv(ga, i) * __builtin_amdgcn_rcpf(gv(gb, i)); } }
;     }
.LBB0_79:
	s_cmpk_eq_i32 s18, 0x400
	s_cselect_b32 s92, 0, 0x800
	v_lshl_add_u64 v[166:167], v[90:91], 0, s[92:93]
	global_load_dwordx2 v[176:177], v[166:167], off
	global_load_dwordx2 v[178:179], v[166:167], off offset:2048
	global_load_dwordx2 v[180:181], v[166:167], off offset:32
	global_load_dwordx2 v[182:183], v[166:167], off offset:2080
	global_load_dwordx2 v[184:185], v[166:167], off offset:256
	global_load_dwordx2 v[186:187], v[166:167], off offset:2304
	global_load_dwordx2 v[188:189], v[166:167], off offset:288
	global_load_dwordx2 v[190:191], v[166:167], off offset:2336
	v_lshl_add_u64 v[166:167], v[86:87], 0, s[92:93]
	global_load_dwordx2 v[192:193], v[166:167], off
	global_load_dwordx2 v[194:195], v[166:167], off offset:2048
	global_load_dwordx2 v[198:199], v[166:167], off offset:32
	global_load_dwordx2 v[200:201], v[166:167], off offset:2080
	global_load_dwordx2 v[202:203], v[166:167], off offset:256
	global_load_dwordx2 v[204:205], v[166:167], off offset:2304
	global_load_dwordx2 v[206:207], v[166:167], off offset:288
	global_load_dwordx2 v[208:209], v[166:167], off offset:2336
	v_lshl_add_u64 v[166:167], v[82:83], 0, s[92:93]
	global_load_dwordx2 v[210:211], v[166:167], off
	global_load_dwordx2 v[212:213], v[166:167], off offset:2048
	global_load_dwordx2 v[214:215], v[166:167], off offset:32
	global_load_dwordx2 v[216:217], v[166:167], off offset:2080
	global_load_dwordx2 v[218:219], v[166:167], off offset:256
	global_load_dwordx2 v[220:221], v[166:167], off offset:2304
	global_load_dwordx2 v[222:223], v[166:167], off offset:288
	global_load_dwordx2 v[224:225], v[166:167], off offset:2336
	v_lshl_add_u64 v[166:167], v[78:79], 0, s[92:93]
	global_load_dwordx2 v[226:227], v[166:167], off
	global_load_dwordx2 v[228:229], v[166:167], off offset:2048
	global_load_dwordx2 v[230:231], v[166:167], off offset:32
	global_load_dwordx2 v[232:233], v[166:167], off offset:2080
	global_load_dwordx2 v[234:235], v[166:167], off offset:256
	global_load_dwordx2 v[236:237], v[166:167], off offset:2304
	global_load_dwordx2 v[110:111], v[166:167], off offset:288
	global_load_dwordx2 v[112:113], v[166:167], off offset:2336
	s_waitcnt vmcnt(30)
	v_lshlrev_b32_e32 v96, 16, v178
	v_and_b32_e32 v97, 0xffff0000, v178
	v_lshlrev_b32_e32 v98, 16, v179
	v_and_b32_e32 v99, 0xffff0000, v179
	v_rcp_f32_e32 v96, v96
	v_rcp_f32_e32 v97, v97
	v_rcp_f32_e32 v98, v98
	v_rcp_f32_e32 v99, v99
	v_lshlrev_b32_e32 v105, 16, v176
	v_and_b32_e32 v106, 0xffff0000, v176
	v_lshlrev_b32_e32 v107, 16, v177
	v_and_b32_e32 v108, 0xffff0000, v177
	v_mul_f32_e32 v105, v96, v105
	v_mul_f32_e32 v106, v97, v106
	v_mul_f32_e32 v107, v98, v107
	v_mul_f32_e32 v108, v99, v108
	v_mul_f32_e32 v62, v62, v105
	v_mul_f32_e32 v63, v63, v106
	v_mul_f32_e32 v64, v64, v107
	v_mul_f32_e32 v65, v65, v108
	s_waitcnt vmcnt(28)
	v_lshlrev_b32_e32 v96, 16, v182
	v_and_b32_e32 v97, 0xffff0000, v182
	v_lshlrev_b32_e32 v98, 16, v183
	v_and_b32_e32 v99, 0xffff0000, v183
	v_rcp_f32_e32 v96, v96
	v_rcp_f32_e32 v97, v97
	v_rcp_f32_e32 v98, v98
	v_rcp_f32_e32 v99, v99
	v_lshlrev_b32_e32 v105, 16, v180
	v_and_b32_e32 v106, 0xffff0000, v180
	v_lshlrev_b32_e32 v107, 16, v181
	v_and_b32_e32 v108, 0xffff0000, v181
	v_mul_f32_e32 v105, v96, v105
	v_mul_f32_e32 v106, v97, v106
	v_mul_f32_e32 v107, v98, v107
	v_mul_f32_e32 v108, v99, v108
	v_mul_f32_e32 v58, v58, v105
	v_mul_f32_e32 v59, v59, v106
	v_mul_f32_e32 v60, v60, v107
	v_mul_f32_e32 v61, v61, v108
	s_waitcnt vmcnt(26)
	v_lshlrev_b32_e32 v96, 16, v186
	v_and_b32_e32 v97, 0xffff0000, v186
	v_lshlrev_b32_e32 v98, 16, v187
	v_and_b32_e32 v99, 0xffff0000, v187
	v_rcp_f32_e32 v96, v96
	v_rcp_f32_e32 v97, v97
	v_rcp_f32_e32 v98, v98
	v_rcp_f32_e32 v99, v99
	v_lshlrev_b32_e32 v105, 16, v184
	v_and_b32_e32 v106, 0xffff0000, v184
	v_lshlrev_b32_e32 v107, 16, v185
	v_and_b32_e32 v108, 0xffff0000, v185
	v_mul_f32_e32 v105, v96, v105
	v_mul_f32_e32 v106, v97, v106
	v_mul_f32_e32 v107, v98, v107
	v_mul_f32_e32 v108, v99, v108
	v_mul_f32_e32 v54, v54, v105
	v_mul_f32_e32 v55, v55, v106
	v_mul_f32_e32 v56, v56, v107
	v_mul_f32_e32 v57, v57, v108
	s_waitcnt vmcnt(24)
	v_lshlrev_b32_e32 v96, 16, v190
	v_and_b32_e32 v97, 0xffff0000, v190
	v_lshlrev_b32_e32 v98, 16, v191
	v_and_b32_e32 v99, 0xffff0000, v191
	v_rcp_f32_e32 v96, v96
	v_rcp_f32_e32 v97, v97
	v_rcp_f32_e32 v98, v98
	v_rcp_f32_e32 v99, v99
	v_lshlrev_b32_e32 v105, 16, v188
	v_and_b32_e32 v106, 0xffff0000, v188
	v_lshlrev_b32_e32 v107, 16, v189
	v_and_b32_e32 v108, 0xffff0000, v189
	v_mul_f32_e32 v105, v96, v105
	v_mul_f32_e32 v106, v97, v106
	v_mul_f32_e32 v107, v98, v107
	v_mul_f32_e32 v108, v99, v108
	v_mul_f32_e32 v50, v50, v105
	v_mul_f32_e32 v51, v51, v106
	v_mul_f32_e32 v52, v52, v107
	v_mul_f32_e32 v53, v53, v108
	s_waitcnt vmcnt(22)
	v_lshlrev_b32_e32 v96, 16, v194
	v_and_b32_e32 v97, 0xffff0000, v194
	v_lshlrev_b32_e32 v98, 16, v195
	v_and_b32_e32 v99, 0xffff0000, v195
	v_rcp_f32_e32 v96, v96
	v_rcp_f32_e32 v97, v97
	v_rcp_f32_e32 v98, v98
	v_rcp_f32_e32 v99, v99
	v_lshlrev_b32_e32 v105, 16, v192
	v_and_b32_e32 v106, 0xffff0000, v192
	v_lshlrev_b32_e32 v107, 16, v193
	v_and_b32_e32 v108, 0xffff0000, v193
	v_mul_f32_e32 v105, v96, v105
	v_mul_f32_e32 v106, v97, v106
	v_mul_f32_e32 v107, v98, v107
	v_mul_f32_e32 v108, v99, v108
	v_mul_f32_e32 v46, v46, v105
	v_mul_f32_e32 v47, v47, v106
	v_mul_f32_e32 v48, v48, v107
	v_mul_f32_e32 v49, v49, v108
	s_waitcnt vmcnt(20)
;     static __device__ __forceinline__ float gv(unsigned long long gw, int i) { return __uint_as_float((unsigned)((gw >> (16 * i)) & 0xffffull) << 16); }
;     __device__ __forceinline__ void khook(f32x4 (&acc)[2][2][4][2], const Unit& u, int t, int wr, int wc, int fr, int fq) const {
;     ...
;                     for (int n = 0; n < 2; ++n) { const int c = col0 + bj * HALF + n * 16; const bf16_t* gp = G + row * ldg + c + br * 1024;
;                         const unsigned long long ga = *(const unsigned long long*)gp, gb = *(const unsigned long long*)(gp + 1024);
; #pragma unroll
;                         for (int i = 0; i < 4; ++i) acc[ai][bj][m][n][i] *= gv(ga, i) * __builtin_amdgcn_rcpf(gv(gb, i)); } }
	v_lshlrev_b32_e32 v96, 16, v200
	v_and_b32_e32 v97, 0xffff0000, v200
	v_lshlrev_b32_e32 v98, 16, v201
	v_and_b32_e32 v99, 0xffff0000, v201
	v_rcp_f32_e32 v96, v96
	v_rcp_f32_e32 v97, v97
	v_rcp_f32_e32 v98, v98
	v_rcp_f32_e32 v99, v99
	v_lshlrev_b32_e32 v105, 16, v198
	v_and_b32_e32 v106, 0xffff0000, v198
	v_lshlrev_b32_e32 v107, 16, v199
	v_and_b32_e32 v108, 0xffff0000, v199
	v_mul_f32_e32 v105, v96, v105
	v_mul_f32_e32 v106, v97, v106
	v_mul_f32_e32 v107, v98, v107
	v_mul_f32_e32 v108, v99, v108
	v_mul_f32_e32 v42, v42, v105
	v_mul_f32_e32 v43, v43, v106
	v_mul_f32_e32 v44, v44, v107
	v_mul_f32_e32 v45, v45, v108
	s_waitcnt vmcnt(18)
	v_lshlrev_b32_e32 v96, 16, v204
	v_and_b32_e32 v97, 0xffff0000, v204
	v_lshlrev_b32_e32 v98, 16, v205
	v_and_b32_e32 v99, 0xffff0000, v205
	v_rcp_f32_e32 v96, v96
	v_rcp_f32_e32 v97, v97
	v_rcp_f32_e32 v98, v98
	v_rcp_f32_e32 v99, v99
	v_lshlrev_b32_e32 v105, 16, v202
	v_and_b32_e32 v106, 0xffff0000, v202
	v_lshlrev_b32_e32 v107, 16, v203
	v_and_b32_e32 v108, 0xffff0000, v203
	v_mul_f32_e32 v105, v96, v105
	v_mul_f32_e32 v106, v97, v106
	v_mul_f32_e32 v107, v98, v107
	v_mul_f32_e32 v108, v99, v108
	v_mul_f32_e32 v38, v38, v105
	v_mul_f32_e32 v39, v39, v106
	v_mul_f32_e32 v40, v40, v107
	v_mul_f32_e32 v41, v41, v108
	s_waitcnt vmcnt(16)
	v_lshlrev_b32_e32 v96, 16, v208
	v_and_b32_e32 v97, 0xffff0000, v208
	v_lshlrev_b32_e32 v98, 16, v209
	v_and_b32_e32 v99, 0xffff0000, v209
	v_rcp_f32_e32 v96, v96
	v_rcp_f32_e32 v97, v97
	v_rcp_f32_e32 v98, v98
	v_rcp_f32_e32 v99, v99
	v_lshlrev_b32_e32 v105, 16, v206
	v_and_b32_e32 v106, 0xffff0000, v206
	v_lshlrev_b32_e32 v107, 16, v207
	v_and_b32_e32 v108, 0xffff0000, v207
	v_mul_f32_e32 v105, v96, v105
	v_mul_f32_e32 v106, v97, v106
	v_mul_f32_e32 v107, v98, v107
	v_mul_f32_e32 v108, v99, v108
	v_mul_f32_e32 v34, v34, v105
	v_mul_f32_e32 v35, v35, v106
	v_mul_f32_e32 v36, v36, v107
	v_mul_f32_e32 v37, v37, v108
	s_waitcnt vmcnt(14)
	v_lshlrev_b32_e32 v96, 16, v212
	v_and_b32_e32 v97, 0xffff0000, v212
	v_lshlrev_b32_e32 v98, 16, v213
	v_and_b32_e32 v99, 0xffff0000, v213
	v_rcp_f32_e32 v96, v96
	v_rcp_f32_e32 v97, v97
	v_rcp_f32_e32 v98, v98
	v_rcp_f32_e32 v99, v99
	v_lshlrev_b32_e32 v105, 16, v210
	v_and_b32_e32 v106, 0xffff0000, v210
	v_lshlrev_b32_e32 v107, 16, v211
	v_and_b32_e32 v108, 0xffff0000, v211
	v_mul_f32_e32 v105, v96, v105
	v_mul_f32_e32 v106, v97, v106
	v_mul_f32_e32 v107, v98, v107
	v_mul_f32_e32 v108, v99, v108
	v_mul_f32_e32 v30, v30, v105
	v_mul_f32_e32 v31, v31, v106
	v_mul_f32_e32 v32, v32, v107
	v_mul_f32_e32 v33, v33, v108
	s_waitcnt vmcnt(12)
	v_lshlrev_b32_e32 v96, 16, v216
	v_and_b32_e32 v97, 0xffff0000, v216
	v_lshlrev_b32_e32 v98, 16, v217
	v_and_b32_e32 v99, 0xffff0000, v217
	v_rcp_f32_e32 v96, v96
	v_rcp_f32_e32 v97, v97
	v_rcp_f32_e32 v98, v98
	v_rcp_f32_e32 v99, v99
	v_lshlrev_b32_e32 v105, 16, v214
	v_and_b32_e32 v106, 0xffff0000, v214
	v_lshlrev_b32_e32 v107, 16, v215
	v_and_b32_e32 v108, 0xffff0000, v215
	v_mul_f32_e32 v105, v96, v105
	v_mul_f32_e32 v106, v97, v106
	v_mul_f32_e32 v107, v98, v107
	v_mul_f32_e32 v108, v99, v108
	v_mul_f32_e32 v26, v26, v105
	v_mul_f32_e32 v27, v27, v106
	v_mul_f32_e32 v28, v28, v107
	v_mul_f32_e32 v29, v29, v108
	s_waitcnt vmcnt(10)
;     static __device__ __forceinline__ float gv(unsigned long long gw, int i) { return __uint_as_float((unsigned)((gw >> (16 * i)) & 0xffffull) << 16); }
;     __device__ __forceinline__ void khook(f32x4 (&acc)[2][2][4][2], const Unit& u, int t, int wr, int wc, int fr, int fq) const {
;     ...
;                     for (int n = 0; n < 2; ++n) { const int c = col0 + bj * HALF + n * 16; const bf16_t* gp = G + row * ldg + c + br * 1024;
;                         const unsigned long long ga = *(const unsigned long long*)gp, gb = *(const unsigned long long*)(gp + 1024);
; #pragma unroll
;                         for (int i = 0; i < 4; ++i) acc[ai][bj][m][n][i] *= gv(ga, i) * __builtin_amdgcn_rcpf(gv(gb, i)); } }
; template <class Epi, class Sched, bool ALIGN_EPI = false, bool SP2 = false, bool HALFM = false>
; __device__ __forceinline__ void gemm_phase(PG8_LAS unsigned char* lds, const Gemm g, const Sched& S, const Epi& E, const int tid_in) {
;     ...
;             if constexpr (Epi::KHOOK) { if (t == 8 || t == 16) E.khook(acc, cur, t, wr, wc, fr, fq); }
	v_lshlrev_b32_e32 v96, 16, v220
	v_and_b32_e32 v97, 0xffff0000, v220
	v_lshlrev_b32_e32 v98, 16, v221
	v_and_b32_e32 v99, 0xffff0000, v221
	v_rcp_f32_e32 v96, v96
	v_rcp_f32_e32 v97, v97
	v_rcp_f32_e32 v98, v98
	v_rcp_f32_e32 v99, v99
	v_lshlrev_b32_e32 v105, 16, v218
	v_and_b32_e32 v106, 0xffff0000, v218
	v_lshlrev_b32_e32 v107, 16, v219
	v_and_b32_e32 v108, 0xffff0000, v219
	v_mul_f32_e32 v105, v96, v105
	v_mul_f32_e32 v106, v97, v106
	v_mul_f32_e32 v107, v98, v107
	v_mul_f32_e32 v108, v99, v108
	v_mul_f32_e32 v22, v22, v105
	v_mul_f32_e32 v23, v23, v106
	v_mul_f32_e32 v24, v24, v107
	v_mul_f32_e32 v25, v25, v108
	s_waitcnt vmcnt(8)
	v_lshlrev_b32_e32 v96, 16, v224
	v_and_b32_e32 v97, 0xffff0000, v224
	v_lshlrev_b32_e32 v98, 16, v225
	v_and_b32_e32 v99, 0xffff0000, v225
	v_rcp_f32_e32 v96, v96
	v_rcp_f32_e32 v97, v97
	v_rcp_f32_e32 v98, v98
	v_rcp_f32_e32 v99, v99
	v_lshlrev_b32_e32 v105, 16, v222
	v_and_b32_e32 v106, 0xffff0000, v222
	v_lshlrev_b32_e32 v107, 16, v223
	v_and_b32_e32 v108, 0xffff0000, v223
	v_mul_f32_e32 v105, v96, v105
	v_mul_f32_e32 v106, v97, v106
	v_mul_f32_e32 v107, v98, v107
	v_mul_f32_e32 v108, v99, v108
	v_mul_f32_e32 v18, v18, v105
	v_mul_f32_e32 v19, v19, v106
	v_mul_f32_e32 v20, v20, v107
	v_mul_f32_e32 v21, v21, v108
	s_waitcnt vmcnt(6)
	v_lshlrev_b32_e32 v96, 16, v228
	v_and_b32_e32 v97, 0xffff0000, v228
	v_lshlrev_b32_e32 v98, 16, v229
	v_and_b32_e32 v99, 0xffff0000, v229
	v_rcp_f32_e32 v96, v96
	v_rcp_f32_e32 v97, v97
	v_rcp_f32_e32 v98, v98
	v_rcp_f32_e32 v99, v99
	v_lshlrev_b32_e32 v105, 16, v226
	v_and_b32_e32 v106, 0xffff0000, v226
	v_lshlrev_b32_e32 v107, 16, v227
	v_and_b32_e32 v108, 0xffff0000, v227
	v_mul_f32_e32 v105, v96, v105
	v_mul_f32_e32 v106, v97, v106
	v_mul_f32_e32 v107, v98, v107
	v_mul_f32_e32 v108, v99, v108
	v_mul_f32_e32 v14, v14, v105
	v_mul_f32_e32 v15, v15, v106
	v_mul_f32_e32 v16, v16, v107
	v_mul_f32_e32 v17, v17, v108
	s_waitcnt vmcnt(4)
	v_lshlrev_b32_e32 v96, 16, v232
	v_and_b32_e32 v97, 0xffff0000, v232
	v_lshlrev_b32_e32 v98, 16, v233
	v_and_b32_e32 v99, 0xffff0000, v233
	v_rcp_f32_e32 v96, v96
	v_rcp_f32_e32 v97, v97
	v_rcp_f32_e32 v98, v98
	v_rcp_f32_e32 v99, v99
	v_lshlrev_b32_e32 v105, 16, v230
	v_and_b32_e32 v106, 0xffff0000, v230
	v_lshlrev_b32_e32 v107, 16, v231
	v_and_b32_e32 v108, 0xffff0000, v231
	v_mul_f32_e32 v105, v96, v105
	v_mul_f32_e32 v106, v97, v106
	v_mul_f32_e32 v107, v98, v107
	v_mul_f32_e32 v108, v99, v108
	v_mul_f32_e32 v10, v10, v105
	v_mul_f32_e32 v11, v11, v106
	v_mul_f32_e32 v12, v12, v107
	v_mul_f32_e32 v13, v13, v108
	s_waitcnt vmcnt(2)
	v_lshlrev_b32_e32 v96, 16, v236
	v_and_b32_e32 v97, 0xffff0000, v236
	v_lshlrev_b32_e32 v98, 16, v237
	v_and_b32_e32 v99, 0xffff0000, v237
	v_rcp_f32_e32 v96, v96
	v_rcp_f32_e32 v97, v97
	v_rcp_f32_e32 v98, v98
	v_rcp_f32_e32 v99, v99
	v_lshlrev_b32_e32 v105, 16, v234
	v_and_b32_e32 v106, 0xffff0000, v234
	v_lshlrev_b32_e32 v107, 16, v235
	v_and_b32_e32 v108, 0xffff0000, v235
	v_mul_f32_e32 v105, v96, v105
	v_mul_f32_e32 v106, v97, v106
	v_mul_f32_e32 v107, v98, v107
	v_mul_f32_e32 v108, v99, v108
	v_mul_f32_e32 v6, v6, v105
	v_mul_f32_e32 v7, v7, v106
	v_mul_f32_e32 v8, v8, v107
	v_mul_f32_e32 v9, v9, v108
	s_waitcnt vmcnt(0)
	v_lshlrev_b32_e32 v96, 16, v112
	v_and_b32_e32 v97, 0xffff0000, v112
	v_lshlrev_b32_e32 v98, 16, v113
	v_and_b32_e32 v99, 0xffff0000, v113
	v_rcp_f32_e32 v96, v96
	v_rcp_f32_e32 v97, v97
	v_rcp_f32_e32 v98, v98
	v_rcp_f32_e32 v99, v99
	v_lshlrev_b32_e32 v105, 16, v110
	v_and_b32_e32 v106, 0xffff0000, v110
	v_lshlrev_b32_e32 v107, 16, v111
	v_and_b32_e32 v108, 0xffff0000, v111
	v_mul_f32_e32 v105, v96, v105
	v_mul_f32_e32 v106, v97, v106
	v_mul_f32_e32 v107, v98, v107
	v_mul_f32_e32 v108, v99, v108
	v_mul_f32_e32 v2, v2, v105
	v_mul_f32_e32 v3, v3, v106
	v_mul_f32_e32 v4, v4, v107
	v_mul_f32_e32 v5, v5, v108
	s_branch .LBB0_71
